# same as previous, the role-1 invalidate skip is taken only when the census verified exactly two workgroups on each of 256 CUs
# baseline (speedup 1.0000x reference)
; __device__ __forceinline__ unsigned xb_ld(unsigned* p) { return __hip_atomic_load(p, __ATOMIC_RELAXED, __HIP_MEMORY_SCOPE_AGENT); }
; #define XB_SPIN(cond, bar) do { unsigned _sp = 0; while (cond) { __builtin_amdgcn_s_sleep(0); \
;     if ((++_sp & 255u) == 0u) { if (xb_ld(&(bar)[XB_TMO])) break; if (_sp > XB_SPIN_CAP) { atomicAdd(&(bar)[XB_TMO], 1u); break; } } } } while (0)
; __device__ __forceinline__ void xcd_barrier(XcdBarrier& b, const int tid, const unsigned G) {
;     ...
;     } else {
;       XB_SPIN(xb_ld(&bar[XB_XGEN(b.x)]) == gen, bar);
;       __builtin_amdgcn_fence(__ATOMIC_ACQUIRE, "agent");
;       asm volatile("s_waitcnt vmcnt(0)" ::: "memory");
; __global__ void __launch_bounds__(256, 2) hymba_fwd(Params p_, int ph_lo, int ph_hi) {
;     ...
;       nprim = (int)xb_ld(&xb.bar[CEN_CNT]); nsec = (int)xb_ld(&xb.bar[CEN_CNT + 1]);
;       if (role != 0) { const unsigned v = xb_ld(&xb.bar[CEN_TAB2 + (unsigned)(-1 - ci)]); ci = (v > 0u) ? (int)v - 1 : 0; }
;       nprim = __builtin_amdgcn_readfirstlane(nprim); nsec = __builtin_amdgcn_readfirstlane(nsec); ci = __builtin_amdgcn_readfirstlane(ci);
.Lxb_wait:
	s_cmp_lg_u32 s23, 0
	s_cbranch_scc0 .Lxb_inv
	v_readlane_b32 s23, v254, 15
	s_nop 3
	s_cmpk_lg_i32 s23, 0x100
	s_cbranch_scc1 .Lxb_inv
	v_readlane_b32 s23, v254, 16
	s_nop 3
	s_cmpk_lg_i32 s23, 0x100
	s_cbranch_scc0 .Lxb_spin
